# recurrence fix-up phase: workgroup-to-chunk mapping permuted so each workgroup scans token chunks of M-tiles owned by its own XCD
# baseline (speedup 1.0000x reference)
;   DI bf16_t* h() const { return (bf16_t*)(ws + OFF_H); }
;   DI float* carry() const { return (float*)(ws + OFF_CARRY); }
; DI int otid() { int t = threadIdx.x; asm volatile("" : "+v"(t)); return t; }
; DI void phase_scan_fix(const Params& p) {
;   for (int i = blockIdx.x * NTH + otid(); i < NBATCH * 128 * 256; i += gridDim.x * NTH) {
;     const int ch = (i & 255) * 4, c = (i >> 8) & 127, b = i >> 15;
;     f32x4 h = {0.f, 0.f, 0.f, 0.f};
;     const float* cA = p.carry() + ((size_t)b * 128 * 256 + (i & 255)) * 4;
;     const float* cH = cA + (size_t)NBATCH * 128 * 1024;
;     int cc = 0;
.LBB0_677:
	s_or_b64 exec, exec, s[0:1]
	v_mov_b32_e32 v0, v206
	v_readlane_b32 s0, v252, 37
	s_waitcnt lgkmcnt(0)
	s_barrier
	s_nop 0
	v_add_u32_e32 v96, s0, v0
	s_cmp_lg_u32 s96, 0x100
	s_cbranch_scc1 .Lxr_p5
	s_lshr_b32 s98, s0, 9
	s_and_b32 s99, s98, 0xc0
	s_and_b32 s100, s98, 8
	s_lshl_b32 s100, s100, 2
	s_or_b32 s99, s99, s100
	s_and_b32 s100, s98, 7
	s_lshl_b32 s100, s100, 2
	s_or_b32 s99, s99, s100
	s_bfe_u32 s100, s98, 0x20004
	s_or_b32 s99, s99, s100
	s_lshl_b32 s99, s99, 9
	v_add_u32_e32 v96, s99, v0
.Lxr_p5:
	s_mov_b32 s0, 0x20000
	v_cmp_gt_i32_e32 vcc, s0, v96
	s_and_saveexec_b64 s[0:1], vcc
	s_cbranch_execz .LBB0_690
	s_lshl_b32 s18, s96, 9
	s_add_u32 s4, s22, 0x14ec7000
	s_addc_u32 s5, s23, 0
	s_lshl_b32 s19, s96, 11
	s_add_u32 s8, s22, 0x14cc0000
	s_addc_u32 s9, s23, 0
	v_lshlrev_b32_e32 v0, 2, v0
	s_add_u32 s10, s22, 0x80cf600
	v_lshl_add_u32 v97, s84, 11, v0
	s_addc_u32 s11, s23, 0
	s_mov_b64 s[12:13], 0
	v_mov_b32_e32 v71, 0
	v_mov_b32_e32 v0, 0
	s_movk_i32 s24, 0xa000
	s_movk_i32 s25, 0xc000
	s_movk_i32 s30, 0xe000
	s_mov_b64 s[14:15], 0x8000
	s_mov_b64 s[26:27], 0x1000
	s_mov_b32 s31, 0x2200000
	s_mov_b32 s34, 0x40c1000
	s_mov_b32 s35, 0x40c3000
	s_mov_b32 s36, 0x40c5000
	s_mov_b32 s37, 0x40c6000
	s_mov_b64 s[28:29], 0x11000
	s_mov_b32 s38, 0x1ffff
